# in_proj rstd_prologue: all 9 units' rowsq loads in a single batch (was 6+3), on top of v20
# speedup vs baseline: 1.0078x; 1.0078x over previous
;     __device__ bool next(int i, Unit& u) const { Unit b; if (!so.next(i >> 2, b)) return false; const int sub = i & 3; u.pm = b.pm; u.pn = sub * 4 + b.pn; u.acol = sub * 512; u.ord = i; return true; }
;     __device__ bool next(int i, Unit& u) const {
;         const long L = (long)i * G + c; if (L >= nwg) return false;
;         int wgid = (int)L; { const int q = nwg / NXCD, r = nwg % NXCD, xcd = wgid % NXCD, off = wgid / NXCD; wgid = (xcd < r ? xcd * (q + 1) : r * (q + 1) + (xcd - r) * q) + off; }
;         const int nig = WGM * nN, gid = wgid / nig, fm = gid * WGM, gsz = (nM - fm) < WGM ? (nM - fm) : WGM;
;         u.pm = fm + ((wgid % nig) % gsz); u.pn = (wgid % nig) / gsz; u.acol = 0; u.ord = i; return true;
; __device__ __forceinline__ float row_rstd(const float* rowsq, size_t row) {
;     const f32x4* q = (const f32x4*)(rowsq + row * 16); const f32x4 a = q[0], b = q[1], c = q[2], d = q[3];
;     const float s = ((a[0] + a[1]) + (a[2] + a[3])) + ((b[0] + b[1]) + (b[2] + b[3])) + ((c[0] + c[1]) + (c[2] + c[3])) + ((d[0] + d[1]) + (d[2] + d[3]));
;     return rsqrtf(s * (1.f / DM) + EPS);
.LBB0_406:
	s_or_b64 exec, exec, s[24:25]
	s_add_u32 s2, s2, s94
	s_addc_u32 s3, s3, s34
	v_cmp_gt_i64_e32 vcc, s[2:3], v[192:193]
	s_cbranch_vccnz .Lmy_rsb_0_c6
	s_and_saveexec_b64 s[24:25], s[36:37]
	s_cbranch_execz .LBB0_409
	s_ashr_i32 s26, s2, 31
	s_lshr_b32 s26, s26, 29
	s_add_i32 s26, s2, s26
	s_ashr_i32 s27, s26, 3
	s_and_b32 s26, s26, -8
	s_sub_i32 s26, s2, s26
	s_cmp_lt_i32 s26, 0
	s_movk_i32 s28, 0x121
	s_cselect_b32 s28, s28, 0x120
	s_mul_i32 s26, s26, s28
	s_add_i32 s26, s26, s27
	s_mul_hi_i32 s27, s26, 0x38e38e39
	s_lshr_b32 s28, s27, 31
	s_ashr_i32 s27, s27, 6
	s_add_i32 s27, s27, s28
	s_mul_i32 s28, s27, 0x120
	s_lshl_b32 s27, s27, 3
	s_sub_i32 s26, s26, s28
	s_sub_i32 s28, 64, s27
	s_min_i32 s28, s28, 8
	s_abs_i32 s28, s28
	v_cvt_f32_u32_e32 v120, s28
	s_sub_i32 s30, 0, s28
	s_ashr_i32 s29, s26, 31
	s_abs_i32 s26, s26
	v_rcp_iflag_f32_e32 v120, v120
	s_nop 0
	v_mul_f32_e32 v120, 0x4f7ffffe, v120
	v_cvt_u32_f32_e32 v120, v120
	s_nop 0
	v_readfirstlane_b32 s31, v120
	s_mul_i32 s30, s30, s31
	s_mul_hi_u32 s30, s31, s30
	s_add_i32 s31, s31, s30
	s_mul_hi_u32 s30, s26, s31
	s_mul_i32 s30, s30, s28
	s_sub_i32 s26, s26, s30
	s_sub_i32 s30, s26, s28
	s_cmp_ge_u32 s26, s28
	s_cselect_b32 s26, s30, s26
	s_sub_i32 s30, s26, s28
	s_cmp_ge_u32 s26, s28
	s_cselect_b32 s26, s30, s26
	s_xor_b32 s26, s26, s29
	s_sub_i32 s26, s26, s29
	s_add_i32 s26, s26, s27
	s_ashr_i32 s27, s26, 31
	s_lshl_b64 s[26:27], s[26:27], 14
	v_lshl_add_u64 v[132:133], v[2:3], 0, s[26:27]
	global_load_dwordx4 v[120:123], v[132:133], off offset:48
	global_load_dwordx4 v[124:127], v[132:133], off offset:32
	global_load_dwordx4 v[128:131], v[132:133], off offset:16
	s_nop 0
	global_load_dwordx4 v[132:135], v[132:133], off
.LBB0_409:
	s_or_b64 exec, exec, s[24:25]
	s_add_u32 s2, s2, s94
	s_addc_u32 s3, s3, s34
	v_cmp_gt_i64_e32 vcc, s[2:3], v[192:193]
	s_cbranch_vccnz .Lmy_rsb_0_c7
	s_and_saveexec_b64 s[24:25], s[36:37]
	s_cbranch_execz .LBB0_412
	s_ashr_i32 s26, s2, 31
	s_lshr_b32 s26, s26, 29
	s_add_i32 s26, s2, s26
	s_ashr_i32 s27, s26, 3
	s_and_b32 s26, s26, -8
	s_sub_i32 s26, s2, s26
	s_cmp_lt_i32 s26, 0
	s_movk_i32 s28, 0x121
	s_cselect_b32 s28, s28, 0x120
	s_mul_i32 s26, s26, s28
	s_add_i32 s26, s26, s27
	s_mul_hi_i32 s27, s26, 0x38e38e39
	s_lshr_b32 s28, s27, 31
	s_ashr_i32 s27, s27, 6
	s_add_i32 s27, s27, s28
	s_mul_i32 s28, s27, 0x120
	s_lshl_b32 s27, s27, 3
	s_sub_i32 s26, s26, s28
	s_sub_i32 s28, 64, s27
	s_min_i32 s28, s28, 8
	s_abs_i32 s28, s28
	v_cvt_f32_u32_e32 v136, s28
	s_sub_i32 s30, 0, s28
	s_ashr_i32 s29, s26, 31
	s_abs_i32 s26, s26
	v_rcp_iflag_f32_e32 v136, v136
	s_nop 0
	v_mul_f32_e32 v136, 0x4f7ffffe, v136
	v_cvt_u32_f32_e32 v136, v136
	s_nop 0
	v_readfirstlane_b32 s31, v136
	s_mul_i32 s30, s30, s31
	s_mul_hi_u32 s30, s31, s30
	s_add_i32 s31, s31, s30
	s_mul_hi_u32 s30, s26, s31
	s_mul_i32 s30, s30, s28
	s_sub_i32 s26, s26, s30
	s_sub_i32 s30, s26, s28
	s_cmp_ge_u32 s26, s28
	s_cselect_b32 s26, s30, s26
	s_sub_i32 s30, s26, s28
	s_cmp_ge_u32 s26, s28
	s_cselect_b32 s26, s30, s26
	s_xor_b32 s26, s26, s29
	s_sub_i32 s26, s26, s29
	s_add_i32 s26, s26, s27
	s_ashr_i32 s27, s26, 31
	s_lshl_b64 s[26:27], s[26:27], 14
	v_lshl_add_u64 v[148:149], v[2:3], 0, s[26:27]
	global_load_dwordx4 v[136:139], v[148:149], off offset:48
	global_load_dwordx4 v[140:143], v[148:149], off offset:32
	global_load_dwordx4 v[144:147], v[148:149], off offset:16
	s_nop 0
	global_load_dwordx4 v[148:151], v[148:149], off
.LBB0_412:
	s_or_b64 exec, exec, s[24:25]
	s_add_u32 s2, s2, s94
	s_addc_u32 s3, s3, s34
	v_cmp_gt_i64_e32 vcc, s[2:3], v[192:193]
	s_cbranch_vccnz .Lmy_rsb_0_c8
	s_and_saveexec_b64 s[24:25], s[36:37]
	s_cbranch_execz .LBB0_415
	s_ashr_i32 s26, s2, 31
	s_lshr_b32 s26, s26, 29
	s_add_i32 s26, s2, s26
	s_ashr_i32 s27, s26, 3
	s_and_b32 s26, s26, -8
	s_sub_i32 s26, s2, s26
	s_cmp_lt_i32 s26, 0
	s_movk_i32 s28, 0x121
	s_cselect_b32 s28, s28, 0x120
	s_mul_i32 s26, s26, s28
	s_add_i32 s26, s26, s27
	s_mul_hi_i32 s27, s26, 0x38e38e39
	s_lshr_b32 s28, s27, 31
	s_ashr_i32 s27, s27, 6
	s_add_i32 s27, s27, s28
	s_mul_i32 s28, s27, 0x120
	s_lshl_b32 s27, s27, 3
	s_sub_i32 s26, s26, s28
	s_sub_i32 s28, 64, s27
	s_min_i32 s28, s28, 8
	s_abs_i32 s28, s28
	v_cvt_f32_u32_e32 v152, s28
	s_sub_i32 s30, 0, s28
	s_ashr_i32 s29, s26, 31
	s_abs_i32 s26, s26
	v_rcp_iflag_f32_e32 v152, v152
	s_nop 0
	v_mul_f32_e32 v152, 0x4f7ffffe, v152
	v_cvt_u32_f32_e32 v152, v152
	s_nop 0
	v_readfirstlane_b32 s31, v152
	s_mul_i32 s30, s30, s31
	s_mul_hi_u32 s30, s31, s30
	s_add_i32 s31, s31, s30
	s_mul_hi_u32 s30, s26, s31
	s_mul_i32 s30, s30, s28
	s_sub_i32 s26, s26, s30
	s_sub_i32 s30, s26, s28
	s_cmp_ge_u32 s26, s28
	s_cselect_b32 s26, s30, s26
	s_sub_i32 s30, s26, s28
	s_cmp_ge_u32 s26, s28
	s_cselect_b32 s26, s30, s26
	s_xor_b32 s26, s26, s29
	s_sub_i32 s26, s26, s29
	s_add_i32 s26, s26, s27
	s_ashr_i32 s27, s26, 31
	s_lshl_b64 s[26:27], s[26:27], 14
	v_lshl_add_u64 v[164:165], v[2:3], 0, s[26:27]
	global_load_dwordx4 v[152:155], v[164:165], off offset:48
	global_load_dwordx4 v[156:159], v[164:165], off offset:32
	global_load_dwordx4 v[160:163], v[164:165], off offset:16
	s_nop 0
	global_load_dwordx4 v[164:167], v[164:165], off
	s_or_b64 exec, exec, s[24:25]
.Lmy_rsb_0_c9:
	s_and_saveexec_b64 s[24:25], s[36:37]
	s_cbranch_execz .Lmy_rsb_0_s8
	s_mov_b32 s26, 0x800000
	s_waitcnt vmcnt(2)
	v_add_f32_e32 v156, v156, v157
	v_add_f32_e32 v158, v158, v159
	s_waitcnt vmcnt(0)
	v_mov_b32_e32 v20, v165
	v_mov_b32_e32 v21, v166
	v_mov_b32_e32 v165, v167
	v_mov_b32_e32 v166, v161
	v_mov_b32_e32 v167, v162
	v_mov_b32_e32 v161, v163
	v_pk_add_f32 v[164:165], v[20:21], v[164:165]
	v_pk_add_f32 v[160:161], v[166:167], v[160:161]
	v_pk_add_f32 v[164:165], v[164:165], v[164:165] op_sel:[0,1] op_sel_hi:[1,0]
	v_pk_add_f32 v[160:161], v[160:161], v[160:161] op_sel:[0,1] op_sel_hi:[1,0]
	v_mov_b32_e32 v165, v152
	v_mov_b32_e32 v161, v153
	v_mov_b32_e32 v157, v154
	v_mov_b32_e32 v159, v155
	v_pk_add_f32 v[152:153], v[164:165], v[160:161]
	v_pk_add_f32 v[154:155], v[156:157], v[158:159]
	s_nop 0
	v_pk_add_f32 v[152:153], v[152:153], v[154:155]
	s_nop 0
	v_add_f32_e32 v152, v152, v153
	v_fmamk_f32 v152, v152, 0x3a800000, v218
	v_cmp_gt_f32_e32 vcc, s26, v152
	v_mul_f32_e32 v153, 0x4b800000, v152
	s_nop 0
	v_cndmask_b32_e32 v152, v152, v153, vcc
	v_rsq_f32_e32 v152, v152
	s_nop 0
	v_mul_f32_e32 v153, 0x45800000, v152
	v_cndmask_b32_e32 v152, v152, v153, vcc
	ds_write_b32 v0, v152 offset:8192

; __device__ __forceinline__ float row_rstd(const float* rowsq, size_t row) {
;     const f32x4* q = (const f32x4*)(rowsq + row * 16); const f32x4 a = q[0], b = q[1], c = q[2], d = q[3];
;     const float s = ((a[0] + a[1]) + (a[2] + a[3])) + ((b[0] + b[1]) + (b[2] + b[3])) + ((c[0] + c[1]) + (c[2] + c[3])) + ((d[0] + d[1]) + (d[2] + d[3]));
;     return rsqrtf(s * (1.f / DM) + EPS);
.Lmy_rsb_0_c8:
	s_and_saveexec_b64 s[24:25], s[36:37]
	s_cbranch_execz .Lmy_rsb_0_s7
	s_mov_b32 s26, 0x800000
	s_waitcnt vmcnt(2)
	v_add_f32_e32 v140, v140, v141
	v_add_f32_e32 v142, v142, v143
	s_waitcnt vmcnt(0)
	v_mov_b32_e32 v20, v149
	v_mov_b32_e32 v21, v150
	v_mov_b32_e32 v149, v151
	v_mov_b32_e32 v150, v145
	v_mov_b32_e32 v151, v146
	v_mov_b32_e32 v145, v147
	v_pk_add_f32 v[148:149], v[20:21], v[148:149]
	v_pk_add_f32 v[144:145], v[150:151], v[144:145]
	v_pk_add_f32 v[148:149], v[148:149], v[148:149] op_sel:[0,1] op_sel_hi:[1,0]
	v_pk_add_f32 v[144:145], v[144:145], v[144:145] op_sel:[0,1] op_sel_hi:[1,0]
	v_mov_b32_e32 v149, v136
	v_mov_b32_e32 v145, v137
	v_mov_b32_e32 v141, v138
	v_mov_b32_e32 v143, v139
	v_pk_add_f32 v[136:137], v[148:149], v[144:145]
	v_pk_add_f32 v[138:139], v[140:141], v[142:143]
	s_nop 0
	v_pk_add_f32 v[136:137], v[136:137], v[138:139]
	s_nop 0
	v_add_f32_e32 v136, v136, v137
	v_fmamk_f32 v136, v136, 0x3a800000, v218
	v_cmp_gt_f32_e32 vcc, s26, v136
	v_mul_f32_e32 v137, 0x4b800000, v136
	s_nop 0
	v_cndmask_b32_e32 v136, v136, v137, vcc
	v_rsq_f32_e32 v136, v136
	s_nop 0
	v_mul_f32_e32 v137, 0x45800000, v136
	v_cndmask_b32_e32 v136, v136, v137, vcc
	ds_write_b32 v0, v136 offset:7168

; __device__ __forceinline__ float row_rstd(const float* rowsq, size_t row) {
;     const f32x4* q = (const f32x4*)(rowsq + row * 16); const f32x4 a = q[0], b = q[1], c = q[2], d = q[3];
;     const float s = ((a[0] + a[1]) + (a[2] + a[3])) + ((b[0] + b[1]) + (b[2] + b[3])) + ((c[0] + c[1]) + (c[2] + c[3])) + ((d[0] + d[1]) + (d[2] + d[3]));
;     return rsqrtf(s * (1.f / DM) + EPS);
.Lmy_rsb_0_c7:
	s_and_saveexec_b64 s[24:25], s[36:37]
	s_cbranch_execz .Lmy_rsb_0_s6
	s_mov_b32 s26, 0x800000
	s_waitcnt vmcnt(2)
	v_add_f32_e32 v124, v124, v125
	v_add_f32_e32 v126, v126, v127
	s_waitcnt vmcnt(0)
	v_mov_b32_e32 v20, v133
	v_mov_b32_e32 v21, v134
	v_mov_b32_e32 v133, v135
	v_mov_b32_e32 v134, v129
	v_mov_b32_e32 v135, v130
	v_mov_b32_e32 v129, v131
	v_pk_add_f32 v[132:133], v[20:21], v[132:133]
	v_pk_add_f32 v[128:129], v[134:135], v[128:129]
	v_pk_add_f32 v[132:133], v[132:133], v[132:133] op_sel:[0,1] op_sel_hi:[1,0]
	v_pk_add_f32 v[128:129], v[128:129], v[128:129] op_sel:[0,1] op_sel_hi:[1,0]
	v_mov_b32_e32 v133, v120
	v_mov_b32_e32 v129, v121
	v_mov_b32_e32 v125, v122
	v_mov_b32_e32 v127, v123
	v_pk_add_f32 v[120:121], v[132:133], v[128:129]
	v_pk_add_f32 v[122:123], v[124:125], v[126:127]
	s_nop 0
	v_pk_add_f32 v[120:121], v[120:121], v[122:123]
	s_nop 0
	v_add_f32_e32 v120, v120, v121
	v_fmamk_f32 v120, v120, 0x3a800000, v218
	v_cmp_gt_f32_e32 vcc, s26, v120
	v_mul_f32_e32 v121, 0x4b800000, v120
	s_nop 0
	v_cndmask_b32_e32 v120, v120, v121, vcc
	v_rsq_f32_e32 v120, v120
	s_nop 0
	v_mul_f32_e32 v121, 0x45800000, v120
	v_cndmask_b32_e32 v120, v120, v121, vcc
	ds_write_b32 v0, v120 offset:6144
.Lmy_rsb_0_s6:
	s_or_b64 exec, exec, s[24:25]
.Lmy_rsb_0_c6:
	s_and_saveexec_b64 s[24:25], s[36:37]
	s_cbranch_execz .Lmy_rsb_0_s5
	s_mov_b32 s26, 0x800000
	s_waitcnt vmcnt(2)
	v_add_f32_e32 v108, v108, v109
	v_add_f32_e32 v110, v110, v111
	s_waitcnt vmcnt(0)
	v_mov_b32_e32 v20, v117
	v_mov_b32_e32 v21, v118
	v_mov_b32_e32 v117, v119
	v_mov_b32_e32 v118, v113
	v_mov_b32_e32 v119, v114
	v_mov_b32_e32 v113, v115
	v_pk_add_f32 v[116:117], v[20:21], v[116:117]
	v_pk_add_f32 v[112:113], v[118:119], v[112:113]
	v_pk_add_f32 v[116:117], v[116:117], v[116:117] op_sel:[0,1] op_sel_hi:[1,0]
	v_pk_add_f32 v[112:113], v[112:113], v[112:113] op_sel:[0,1] op_sel_hi:[1,0]
	v_mov_b32_e32 v117, v104
	v_mov_b32_e32 v113, v105
	v_mov_b32_e32 v109, v106
	v_mov_b32_e32 v111, v107
	v_pk_add_f32 v[104:105], v[116:117], v[112:113]
	v_pk_add_f32 v[106:107], v[108:109], v[110:111]
	s_nop 0
	v_pk_add_f32 v[104:105], v[104:105], v[106:107]
	s_nop 0
	v_add_f32_e32 v104, v104, v105
	v_fmamk_f32 v104, v104, 0x3a800000, v218
	v_cmp_gt_f32_e32 vcc, s26, v104
	v_mul_f32_e32 v105, 0x4b800000, v104
	s_nop 0
	v_cndmask_b32_e32 v104, v104, v105, vcc
	v_rsq_f32_e32 v104, v104
	s_nop 0
	v_mul_f32_e32 v105, 0x45800000, v104
	v_cndmask_b32_e32 v104, v104, v105, vcc
	ds_write_b32 v0, v104 offset:5120

;     __device__ bool next(int i, Unit& u) const { Unit b; if (!so.next(i >> 2, b)) return false; const int sub = i & 3; u.pm = b.pm; u.pn = sub * 4 + b.pn; u.acol = sub * 512; u.ord = i; return true; }
;     __device__ bool next(int i, Unit& u) const {
;         const long L = (long)i * G + c; if (L >= nwg) return false;
;         int wgid = (int)L; { const int q = nwg / NXCD, r = nwg % NXCD, xcd = wgid % NXCD, off = wgid / NXCD; wgid = (xcd < r ? xcd * (q + 1) : r * (q + 1) + (xcd - r) * q) + off; }
;         const int nig = WGM * nN, gid = wgid / nig, fm = gid * WGM, gsz = (nM - fm) < WGM ? (nM - fm) : WGM;
;         u.pm = fm + ((wgid % nig) % gsz); u.pn = (wgid % nig) / gsz; u.acol = 0; u.ord = i; return true;
; __device__ __forceinline__ float row_rstd(const float* rowsq, size_t row) {
;     const f32x4* q = (const f32x4*)(rowsq + row * 16); const f32x4 a = q[0], b = q[1], c = q[2], d = q[3];
;     const float s = ((a[0] + a[1]) + (a[2] + a[3])) + ((b[0] + b[1]) + (b[2] + b[3])) + ((c[0] + c[1]) + (c[2] + c[3])) + ((d[0] + d[1]) + (d[2] + d[3]));
;     return rsqrtf(s * (1.f / DM) + EPS);
.LBB0_418:
	s_or_b64 exec, exec, s[24:25]
	s_add_u32 s2, s2, s94
	s_addc_u32 s3, s3, s34
	v_cmp_gt_i64_e32 vcc, s[2:3], v[192:193]
	s_cbranch_vccnz .Lmy_rsb_9_c1
	s_and_saveexec_b64 s[24:25], s[36:37]
	s_cbranch_execz .LBB0_421
	s_ashr_i32 s26, s2, 31
	s_lshr_b32 s26, s26, 29
	s_add_i32 s26, s2, s26
	s_ashr_i32 s27, s26, 3
	s_and_b32 s26, s26, -8
	s_sub_i32 s26, s2, s26
	s_cmp_lt_i32 s26, 0
	s_movk_i32 s28, 0x121
	s_cselect_b32 s28, s28, 0x120
	s_mul_i32 s26, s26, s28
	s_add_i32 s26, s26, s27
	s_mul_hi_i32 s27, s26, 0x38e38e39
	s_lshr_b32 s28, s27, 31
	s_ashr_i32 s27, s27, 6
	s_add_i32 s27, s27, s28
	s_mul_i32 s28, s27, 0x120
	s_lshl_b32 s27, s27, 3
	s_sub_i32 s26, s26, s28
	s_sub_i32 s28, 64, s27
	s_min_i32 s28, s28, 8
	s_abs_i32 s28, s28
	v_cvt_f32_u32_e32 v40, s28
	s_sub_i32 s30, 0, s28
	s_ashr_i32 s29, s26, 31
	s_abs_i32 s26, s26
	v_rcp_iflag_f32_e32 v40, v40
	s_nop 0
	v_mul_f32_e32 v40, 0x4f7ffffe, v40
	v_cvt_u32_f32_e32 v40, v40
	s_nop 0
	v_readfirstlane_b32 s31, v40
	s_mul_i32 s30, s30, s31
	s_mul_hi_u32 s30, s31, s30
	s_add_i32 s31, s31, s30
	s_mul_hi_u32 s30, s26, s31
	s_mul_i32 s30, s30, s28
	s_sub_i32 s26, s26, s30
	s_sub_i32 s30, s26, s28
	s_cmp_ge_u32 s26, s28
	s_cselect_b32 s26, s30, s26
	s_sub_i32 s30, s26, s28
	s_cmp_ge_u32 s26, s28
	s_cselect_b32 s26, s30, s26
	s_xor_b32 s26, s26, s29
	s_sub_i32 s26, s26, s29
	s_add_i32 s26, s26, s27
	s_ashr_i32 s27, s26, 31
	s_lshl_b64 s[26:27], s[26:27], 14
	v_lshl_add_u64 v[52:53], v[2:3], 0, s[26:27]
	global_load_dwordx4 v[40:43], v[52:53], off offset:48
	global_load_dwordx4 v[44:47], v[52:53], off offset:32
	global_load_dwordx4 v[48:51], v[52:53], off offset:16
	s_nop 0
	global_load_dwordx4 v[52:55], v[52:53], off
	s_or_b64 exec, exec, s[24:25]
.Lmy_rsb_9_c2:
	s_and_saveexec_b64 s[24:25], s[36:37]
	s_cbranch_execz .Lmy_rsb_9_s1
	s_mov_b32 s26, 0x800000
	s_waitcnt vmcnt(2)
	v_add_f32_e32 v44, v44, v45
	v_add_f32_e32 v46, v46, v47
	s_waitcnt vmcnt(0)
	v_mov_b32_e32 v20, v53
	v_mov_b32_e32 v21, v54
	v_mov_b32_e32 v53, v55
	v_mov_b32_e32 v54, v49
	v_mov_b32_e32 v55, v50
	v_mov_b32_e32 v49, v51
	v_pk_add_f32 v[52:53], v[20:21], v[52:53]
	v_pk_add_f32 v[48:49], v[54:55], v[48:49]
	v_pk_add_f32 v[52:53], v[52:53], v[52:53] op_sel:[0,1] op_sel_hi:[1,0]
	v_pk_add_f32 v[48:49], v[48:49], v[48:49] op_sel:[0,1] op_sel_hi:[1,0]
	v_mov_b32_e32 v53, v40
	v_mov_b32_e32 v49, v41
	v_mov_b32_e32 v45, v42
	v_mov_b32_e32 v47, v43
	v_pk_add_f32 v[40:41], v[52:53], v[48:49]
	v_pk_add_f32 v[42:43], v[44:45], v[46:47]
	s_nop 0
	v_pk_add_f32 v[40:41], v[40:41], v[42:43]
	s_nop 0
	v_add_f32_e32 v40, v40, v41
	v_fmamk_f32 v40, v40, 0x3a800000, v218
	v_cmp_gt_f32_e32 vcc, s26, v40
	v_mul_f32_e32 v41, 0x4b800000, v40
	s_nop 0
	v_cndmask_b32_e32 v40, v40, v41, vcc
	v_rsq_f32_e32 v40, v40
	s_nop 0
	v_mul_f32_e32 v41, 0x45800000, v40
	v_cndmask_b32_e32 v40, v40, v41, vcc
	ds_write_b32 v0, v40 offset:10240

; __device__ __forceinline__ float row_rstd(const float* rowsq, size_t row) {
;     const f32x4* q = (const f32x4*)(rowsq + row * 16); const f32x4 a = q[0], b = q[1], c = q[2], d = q[3];
;     const float s = ((a[0] + a[1]) + (a[2] + a[3])) + ((b[0] + b[1]) + (b[2] + b[3])) + ((c[0] + c[1]) + (c[2] + c[3])) + ((d[0] + d[1]) + (d[2] + d[3]));
;     return rsqrtf(s * (1.f / DM) + EPS);
.Lmy_rsb_9_c1:
	s_and_saveexec_b64 s[24:25], s[36:37]
	s_cbranch_execz .Lmy_rsb_9_s0
	s_mov_b32 s26, 0x800000
	s_waitcnt vmcnt(2)
	v_add_f32_e32 v28, v28, v29
	v_add_f32_e32 v30, v30, v31
	s_waitcnt vmcnt(0)
	v_mov_b32_e32 v20, v37
	v_mov_b32_e32 v21, v38
	v_mov_b32_e32 v37, v39
	v_mov_b32_e32 v38, v33
	v_mov_b32_e32 v39, v34
	v_mov_b32_e32 v33, v35
	v_pk_add_f32 v[36:37], v[20:21], v[36:37]
	v_pk_add_f32 v[32:33], v[38:39], v[32:33]
	v_pk_add_f32 v[36:37], v[36:37], v[36:37] op_sel:[0,1] op_sel_hi:[1,0]
	v_pk_add_f32 v[32:33], v[32:33], v[32:33] op_sel:[0,1] op_sel_hi:[1,0]
	v_mov_b32_e32 v37, v24
	v_mov_b32_e32 v33, v25
	v_mov_b32_e32 v29, v26
	v_mov_b32_e32 v31, v27
	v_pk_add_f32 v[24:25], v[36:37], v[32:33]
	v_pk_add_f32 v[26:27], v[28:29], v[30:31]
	s_nop 0
	v_pk_add_f32 v[24:25], v[24:25], v[26:27]
	s_nop 0
	v_add_f32_e32 v24, v24, v25
	v_fmamk_f32 v24, v24, 0x3a800000, v218
	v_cmp_gt_f32_e32 vcc, s26, v24
	v_mul_f32_e32 v25, 0x4b800000, v24
	s_nop 0
	v_cndmask_b32_e32 v24, v24, v25, vcc
	v_rsq_f32_e32 v24, v24
	s_nop 0
	v_mul_f32_e32 v25, 0x45800000, v24
	v_cndmask_b32_e32 v24, v24, v25, vcc
	ds_write_b32 v0, v24 offset:9216
